# S5 load_u (both passes) loads issued together with counted waits; GLU weight-fragment loads hoisted ahead of the 8 MFMA rounds
# baseline (speedup 1.0000x reference)
.LBB0_234:
	s_lshl_b32 s14, s7, 6
	v_add_u32_e32 v0, s14, v46
	v_mov_b64_e32 v[4:5], s[36:37]
	v_mad_i64_i32 v[0:1], s[8:9], v0, s75, v[4:5]
	v_mov_b32_e32 v39, v161
	v_lshl_add_u64 v[0:1], v[0:1], 0, v[38:39]
	v_add_co_u32_e32 v0, vcc, 0x1000, v0
	s_mov_b32 s1, 0
	s_nop 0
	v_addc_co_u32_e32 v1, vcc, 0, v1, vcc
	global_load_dwordx4 v[120:123], v[0:1], off
	s_mov_b64 s[38:39], -1
	v_add_u32_e32 v0, s14, v48
	v_mad_i64_i32 v[0:1], s[8:9], v0, s75, v[4:5]
	v_lshl_add_u64 v[0:1], v[0:1], 0, v[38:39]
	v_add_co_u32_e32 v0, vcc, 0x1000, v0
	s_nop 1
	v_addc_co_u32_e32 v1, vcc, 0, v1, vcc
	global_load_dwordx4 v[124:127], v[0:1], off
	v_add_u32_e32 v0, s14, v50
	v_mad_i64_i32 v[0:1], s[8:9], v0, s75, v[4:5]
	v_lshl_add_u64 v[0:1], v[0:1], 0, v[38:39]
	v_add_co_u32_e32 v0, vcc, 0x1000, v0
	s_nop 1
	v_addc_co_u32_e32 v1, vcc, 0, v1, vcc
	global_load_dwordx4 v[128:131], v[0:1], off
	v_add_u32_e32 v0, s14, v52
	v_mad_i64_i32 v[0:1], s[8:9], v0, s75, v[4:5]
	v_lshl_add_u64 v[0:1], v[0:1], 0, v[38:39]
	v_add_co_u32_e32 v0, vcc, 0x1000, v0
	s_nop 1
	v_addc_co_u32_e32 v1, vcc, 0, v1, vcc
	global_load_dwordx4 v[132:135], v[0:1], off
	v_add_u32_e32 v0, s14, v54
	v_mad_i64_i32 v[0:1], s[8:9], v0, s75, v[4:5]
	v_lshl_add_u64 v[0:1], v[0:1], 0, v[38:39]
	v_add_co_u32_e32 v0, vcc, 0x1000, v0
	s_nop 1
	v_addc_co_u32_e32 v1, vcc, 0, v1, vcc
	global_load_dwordx4 v[136:139], v[0:1], off
	v_add_u32_e32 v0, s14, v56
	v_mad_i64_i32 v[0:1], s[8:9], v0, s75, v[4:5]
	v_lshl_add_u64 v[0:1], v[0:1], 0, v[38:39]
	v_add_co_u32_e32 v0, vcc, 0x1000, v0
	s_nop 1
	v_addc_co_u32_e32 v1, vcc, 0, v1, vcc
	global_load_dwordx4 v[140:143], v[0:1], off
	v_add_u32_e32 v0, s14, v58
	v_mad_i64_i32 v[0:1], s[8:9], v0, s75, v[4:5]
	v_lshl_add_u64 v[0:1], v[0:1], 0, v[38:39]
	v_add_co_u32_e32 v0, vcc, 0x1000, v0
	s_nop 1
	v_addc_co_u32_e32 v1, vcc, 0, v1, vcc
	global_load_dwordx4 v[144:147], v[0:1], off
	v_add_u32_e32 v0, s14, v60
	v_mad_i64_i32 v[0:1], s[8:9], v0, s75, v[4:5]
	v_lshl_add_u64 v[0:1], v[0:1], 0, v[38:39]
	v_add_co_u32_e32 v0, vcc, 0x1000, v0
	s_lshl_b32 s8, s7, 4
	s_nop 0
	v_addc_co_u32_e32 v1, vcc, 0, v1, vcc
	global_load_dwordx4 v[148:151], v[0:1], off
	s_waitcnt vmcnt(7)
	ds_write_b128 v47, v[120:123]
	s_waitcnt vmcnt(6)
	ds_write_b128 v49, v[124:127]
	s_waitcnt vmcnt(5)
	ds_write_b128 v51, v[128:131]
	s_waitcnt vmcnt(4)
	ds_write_b128 v53, v[132:135]
	s_waitcnt vmcnt(3)
	ds_write_b128 v55, v[136:139]
	s_waitcnt vmcnt(2)
	ds_write_b128 v57, v[140:143]
	s_waitcnt vmcnt(1)
	ds_write_b128 v59, v[144:147]
	s_waitcnt vmcnt(0)
	ds_write_b128 v61, v[148:151]
	s_waitcnt lgkmcnt(0)
	s_barrier

.LBB0_474:
	s_lshl_b32 s52, s40, 6
	v_add_u32_e32 v0, s52, v53
	v_mov_b64_e32 v[4:5], s[42:43]
	v_mad_i64_i32 v[0:1], s[12:13], v0, s75, v[4:5]
	v_mov_b32_e32 v63, v161
	v_lshl_add_u64 v[0:1], v[0:1], 0, v[62:63]
	v_add_co_u32_e32 v0, vcc, 0x1000, v0
	s_lshl_b32 s53, s40, 4
	s_nop 0
	v_addc_co_u32_e32 v1, vcc, 0, v1, vcc
	global_load_dwordx4 v[120:123], v[0:1], off
	s_mov_b64 s[56:57], -1
	s_mov_b32 s1, 0
	v_add_u32_e32 v0, s52, v74
	v_mad_i64_i32 v[0:1], s[12:13], v0, s75, v[4:5]
	v_lshl_add_u64 v[0:1], v[0:1], 0, v[62:63]
	v_add_co_u32_e32 v0, vcc, 0x1000, v0
	s_nop 1
	v_addc_co_u32_e32 v1, vcc, 0, v1, vcc
	global_load_dwordx4 v[124:127], v[0:1], off
	v_add_u32_e32 v0, s52, v77
	v_mad_i64_i32 v[0:1], s[12:13], v0, s75, v[4:5]
	v_lshl_add_u64 v[0:1], v[0:1], 0, v[62:63]
	v_add_co_u32_e32 v0, vcc, 0x1000, v0
	s_nop 1
	v_addc_co_u32_e32 v1, vcc, 0, v1, vcc
	global_load_dwordx4 v[128:131], v[0:1], off
	v_add_u32_e32 v0, s52, v80
	v_mad_i64_i32 v[0:1], s[12:13], v0, s75, v[4:5]
	v_lshl_add_u64 v[0:1], v[0:1], 0, v[62:63]
	v_add_co_u32_e32 v0, vcc, 0x1000, v0
	s_nop 1
	v_addc_co_u32_e32 v1, vcc, 0, v1, vcc
	global_load_dwordx4 v[132:135], v[0:1], off
	v_add_u32_e32 v0, s52, v83
	v_mad_i64_i32 v[0:1], s[12:13], v0, s75, v[4:5]
	v_lshl_add_u64 v[0:1], v[0:1], 0, v[62:63]
	v_add_co_u32_e32 v0, vcc, 0x1000, v0
	s_nop 1
	v_addc_co_u32_e32 v1, vcc, 0, v1, vcc
	global_load_dwordx4 v[136:139], v[0:1], off
	v_add_u32_e32 v0, s52, v86
	v_mad_i64_i32 v[0:1], s[12:13], v0, s75, v[4:5]
	v_lshl_add_u64 v[0:1], v[0:1], 0, v[62:63]
	v_add_co_u32_e32 v0, vcc, 0x1000, v0
	s_nop 1
	v_addc_co_u32_e32 v1, vcc, 0, v1, vcc
	global_load_dwordx4 v[140:143], v[0:1], off
	v_add_u32_e32 v0, s52, v89
	v_mad_i64_i32 v[0:1], s[12:13], v0, s75, v[4:5]
	v_lshl_add_u64 v[0:1], v[0:1], 0, v[62:63]
	v_add_co_u32_e32 v0, vcc, 0x1000, v0
	s_nop 1
	v_addc_co_u32_e32 v1, vcc, 0, v1, vcc
	global_load_dwordx4 v[144:147], v[0:1], off
	v_add_u32_e32 v0, s52, v92
	v_mad_i64_i32 v[0:1], s[12:13], v0, s75, v[4:5]
	v_lshl_add_u64 v[0:1], v[0:1], 0, v[62:63]
	v_add_co_u32_e32 v0, vcc, 0x1000, v0
	s_nop 1
	v_addc_co_u32_e32 v1, vcc, 0, v1, vcc
	global_load_dwordx4 v[148:151], v[0:1], off
	s_waitcnt vmcnt(7)
	ds_write_b128 v73, v[120:123]
	s_waitcnt vmcnt(6)
	ds_write_b128 v76, v[124:127]
	s_waitcnt vmcnt(5)
	ds_write_b128 v79, v[128:131]
	s_waitcnt vmcnt(4)
	ds_write_b128 v82, v[132:135]
	s_waitcnt vmcnt(3)
	ds_write_b128 v85, v[136:139]
	s_waitcnt vmcnt(2)
	ds_write_b128 v88, v[140:143]
	s_waitcnt vmcnt(1)
	ds_write_b128 v91, v[144:147]
	s_waitcnt vmcnt(0)
	ds_write_b128 v94, v[148:151]
	s_waitcnt lgkmcnt(0)
	s_barrier

.LBB0_499:
	v_add_u32_e32 v119, s1, v102
	v_add_u32_e32 v50, 0x10000, v119
	v_add_u32_e32 v132, 0x10210, v119
	v_add_u32_e32 v133, 0x10420, v119
	v_add_u32_e32 v134, 0x10630, v119
	ds_read_b64 v[124:125], v50
	ds_read_b64 v[126:127], v132
	ds_read_b64 v[128:129], v133
	ds_read_b64 v[130:131], v134
	s_waitcnt vmcnt(0)
	v_pk_mul_f32 v[48:49], v[70:71], v[68:69] op_sel:[0,1]
	v_add_u32_e32 v122, s1, v101
	v_pk_fma_f32 v[120:121], v[66:67], v[68:69], v[48:49] neg_lo:[0,0,1] neg_hi:[0,0,1]
	v_pk_fma_f32 v[48:49], v[66:67], v[68:69], v[48:49] op_sel_hi:[1,0,1]
	v_mov_b32_e32 v121, v49
	s_waitcnt lgkmcnt(3)
	v_pk_add_f32 v[48:49], v[120:121], v[124:125]
	v_add_u32_e32 v51, 0x10000, v122
	v_cvt_pk_bf16_f32 v50, v48, v49
	ds_write_b32 v51, v50
	v_pk_mul_f32 v[50:51], v[70:71], v[48:49] op_sel:[0,1]
	s_addk_i32 s1, 0x840
	v_pk_fma_f32 v[120:121], v[66:67], v[48:49], v[50:51] neg_lo:[0,0,1] neg_hi:[0,0,1]
	v_pk_fma_f32 v[48:49], v[66:67], v[48:49], v[50:51] op_sel_hi:[1,0,1]
	v_add_u32_e32 v51, 0x10210, v122
	v_mov_b32_e32 v121, v49
	s_waitcnt lgkmcnt(3)
	v_pk_add_f32 v[48:49], v[120:121], v[126:127]
	v_cvt_pk_bf16_f32 v50, v48, v49
	ds_write_b32 v51, v50
	v_pk_mul_f32 v[50:51], v[70:71], v[48:49] op_sel:[0,1]
	s_cmpk_eq_i32 s1, 0x2100
	v_pk_fma_f32 v[120:121], v[66:67], v[48:49], v[50:51] neg_lo:[0,0,1] neg_hi:[0,0,1]
	v_pk_fma_f32 v[48:49], v[66:67], v[48:49], v[50:51] op_sel_hi:[1,0,1]
	v_add_u32_e32 v51, 0x10420, v122
	v_mov_b32_e32 v121, v49
	s_waitcnt lgkmcnt(3)
	v_pk_add_f32 v[48:49], v[120:121], v[128:129]
	v_cvt_pk_bf16_f32 v50, v48, v49
	ds_write_b32 v51, v50
	v_pk_mul_f32 v[50:51], v[70:71], v[48:49] op_sel:[0,1]
	s_nop 0
	v_pk_fma_f32 v[120:121], v[66:67], v[48:49], v[50:51] neg_lo:[0,0,1] neg_hi:[0,0,1]
	v_pk_fma_f32 v[48:49], v[66:67], v[48:49], v[50:51] op_sel_hi:[1,0,1]
	s_nop 0
	v_mov_b32_e32 v121, v49
	s_waitcnt lgkmcnt(3)
	v_pk_add_f32 v[68:69], v[120:121], v[130:131]
	v_add_u32_e32 v49, 0x10630, v122
	v_cvt_pk_bf16_f32 v48, v68, v69
	ds_write_b32 v49, v48
	s_cbranch_scc0 .LBB0_499
	ds_read_b128 v[48:51], v105
	ds_read_b128 v[120:123], v105 offset:64
	v_lshl_add_u32 v119, s16, 14, v118
	s_add_i32 s16, s16, 1
	s_cmp_eq_u32 s16, 4
	s_waitcnt lgkmcnt(1)
	v_mfma_f32_16x16x32_bf16 v[48:51], v[48:51], v[32:35], 0
	s_waitcnt lgkmcnt(0)
	v_mfma_f32_16x16x32_bf16 v[48:51], v[120:123], v[36:39], v[48:51]
	ds_read_b128 v[120:123], v105 offset:128
	s_waitcnt lgkmcnt(0)
	v_mfma_f32_16x16x32_bf16 v[48:51], v[120:123], v[40:43], v[48:51]
	ds_read_b128 v[120:123], v105 offset:192
	s_waitcnt lgkmcnt(0)
	v_mfma_f32_16x16x32_bf16 v[48:51], v[120:123], v[44:47], v[48:51]
	ds_read2st64_b32 v[120:121], v119 offset1:4
	s_waitcnt lgkmcnt(0)
	s_nop 5
	v_fma_f32 v48, v63, v120, v48
	v_mul_f32_e32 v120, 0x3d372713, v48
	v_mul_f32_e32 v120, v48, v120
	v_fma_f32 v120, v48, v120, v48
	v_mul_f32_e32 v120, 0x3f4c422a, v120
	v_add_f32_e32 v120, v120, v120
	v_mul_f32_e32 v120, 0x3fb8aa3b, v120
	v_exp_f32_e32 v120, v120
	v_mul_f32_e32 v48, 0.5, v48
	v_fma_f32 v49, v63, v121, v49
	v_add_f32_e32 v120, 1.0, v120
	v_div_scale_f32 v122, s[14:15], v120, v120, 2.0
	v_rcp_f32_e32 v123, v122
	s_nop 0
	v_fma_f32 v124, -v122, v123, 1.0
	v_fmac_f32_e32 v123, v124, v123
	v_div_scale_f32 v124, vcc, 2.0, v120, 2.0
	v_mul_f32_e32 v125, v124, v123
	v_fma_f32 v126, -v122, v125, v124
	v_fmac_f32_e32 v125, v126, v123
	v_fma_f32 v122, -v122, v125, v124
	v_div_fmas_f32 v122, v122, v123, v125
	v_div_fixup_f32 v120, v122, v120, 2.0
	v_sub_f32_e32 v120, 1.0, v120
	v_add_f32_e32 v120, 1.0, v120
	v_mul_f32_e32 v48, v48, v120
	v_mul_f32_e32 v120, 0x3d372713, v49
	v_mul_f32_e32 v120, v49, v120
	v_fma_f32 v120, v49, v120, v49
	v_mul_f32_e32 v120, 0x3f4c422a, v120
	v_add_f32_e32 v120, v120, v120
	v_mul_f32_e32 v120, 0x3fb8aa3b, v120
	v_exp_f32_e32 v120, v120
	v_mul_f32_e32 v49, 0.5, v49
	v_add_f32_e32 v120, 1.0, v120
	v_div_scale_f32 v121, s[14:15], v120, v120, 2.0
	v_rcp_f32_e32 v122, v121
	s_nop 0
	v_fma_f32 v123, -v121, v122, 1.0
	v_fmac_f32_e32 v122, v123, v122
	v_div_scale_f32 v123, vcc, 2.0, v120, 2.0
	v_mul_f32_e32 v124, v123, v122
	v_fma_f32 v125, -v121, v124, v123
	v_fmac_f32_e32 v124, v125, v122
	v_fma_f32 v121, -v121, v124, v123
	v_div_fmas_f32 v121, v121, v122, v124
	v_div_fixup_f32 v120, v121, v120, 2.0
	v_sub_f32_e32 v120, 1.0, v120
	v_add_f32_e32 v120, 1.0, v120
	v_mul_f32_e32 v49, v49, v120
	ds_write2st64_b32 v119, v48, v49 offset1:4
	ds_read2st64_b32 v[48:49], v119 offset0:8 offset1:12
	s_waitcnt lgkmcnt(0)
	v_fma_f32 v48, v63, v48, v50
	v_mul_f32_e32 v50, 0x3d372713, v48
	v_mul_f32_e32 v50, v48, v50
	v_fma_f32 v50, v48, v50, v48
	v_mul_f32_e32 v50, 0x3f4c422a, v50
	v_add_f32_e32 v50, v50, v50
	v_mul_f32_e32 v50, 0x3fb8aa3b, v50
	v_exp_f32_e32 v50, v50
	v_fmac_f32_e32 v51, v63, v49
	v_mul_f32_e32 v49, 0x3d372713, v51
	v_mul_f32_e32 v49, v51, v49
	v_add_f32_e32 v50, 1.0, v50
	v_div_scale_f32 v120, s[14:15], v50, v50, 2.0
	v_rcp_f32_e32 v121, v120
	v_fma_f32 v49, v51, v49, v51
	v_mul_f32_e32 v49, 0x3f4c422a, v49
	v_add_f32_e32 v49, v49, v49
	v_fma_f32 v122, -v120, v121, 1.0
	v_fmac_f32_e32 v121, v122, v121
	v_div_scale_f32 v122, vcc, 2.0, v50, 2.0
	v_mul_f32_e32 v123, v122, v121
	v_fma_f32 v124, -v120, v123, v122
	v_fmac_f32_e32 v123, v124, v121
	v_mul_f32_e32 v49, 0x3fb8aa3b, v49
	v_fma_f32 v120, -v120, v123, v122
	v_exp_f32_e32 v49, v49
	v_div_fmas_f32 v120, v120, v121, v123
	v_div_fixup_f32 v50, v120, v50, 2.0
	v_sub_f32_e32 v50, 1.0, v50
	v_mul_f32_e32 v48, 0.5, v48
	v_add_f32_e32 v50, 1.0, v50
	v_add_f32_e32 v49, 1.0, v49
	v_mul_f32_e32 v48, v48, v50
	v_div_scale_f32 v50, s[14:15], v49, v49, 2.0
	v_rcp_f32_e32 v120, v50
	s_nop 0
	v_fma_f32 v121, -v50, v120, 1.0
	v_fmac_f32_e32 v120, v121, v120
	v_div_scale_f32 v121, vcc, 2.0, v49, 2.0
	v_mul_f32_e32 v122, v121, v120
	v_fma_f32 v123, -v50, v122, v121
	v_fmac_f32_e32 v122, v123, v120
	v_fma_f32 v50, -v50, v122, v121
	v_div_fmas_f32 v50, v50, v120, v122
	v_div_fixup_f32 v49, v50, v49, 2.0
	v_sub_f32_e32 v49, 1.0, v49
	v_mul_f32_e32 v50, 0.5, v51
	v_add_f32_e32 v49, 1.0, v49
	v_mul_f32_e32 v49, v50, v49
	ds_write2st64_b32 v119, v48, v49 offset0:8 offset1:12
	s_cbranch_scc0 .LBB0_496
	s_mov_b32 s1, 8
	s_mov_b64 s[56:57], 0
	s_and_b64 vcc, exec, s[12:13]
	s_cbranch_vccz .LBB0_475
	v_add_u32_e32 v0, v72, v99
	s_waitcnt lgkmcnt(0)
	s_barrier
	ds_read_b128 v[0:3], v0
	v_mov_b32_e32 v65, v161
	s_mov_b32 s1, 0x5000000
	s_add_i32 s40, s40, s34
	s_cmpk_gt_i32 s40, 0xff
	s_waitcnt lgkmcnt(0)
	v_cvt_pk_bf16_f32 v0, v0, v1
	v_cvt_pk_bf16_f32 v1, v2, v3
	ds_write_b64 v106, v[0:1]
	v_add_u32_e32 v0, v75, v99
	ds_read_b128 v[0:3], v0
	s_waitcnt lgkmcnt(0)
	v_cvt_pk_bf16_f32 v0, v0, v1
	v_cvt_pk_bf16_f32 v1, v2, v3
	ds_write_b64 v107, v[0:1]
	v_add_u32_e32 v0, v78, v99
	ds_read_b128 v[0:3], v0
	s_waitcnt lgkmcnt(0)
	v_cvt_pk_bf16_f32 v0, v0, v1
	v_cvt_pk_bf16_f32 v1, v2, v3
	ds_write_b64 v108, v[0:1]
	v_add_u32_e32 v0, v81, v99
	ds_read_b128 v[0:3], v0
	s_waitcnt lgkmcnt(0)
	v_cvt_pk_bf16_f32 v0, v0, v1
	v_cvt_pk_bf16_f32 v1, v2, v3
	ds_write_b64 v109, v[0:1]
	v_add_u32_e32 v0, v84, v99
	ds_read_b128 v[0:3], v0
	s_waitcnt lgkmcnt(0)
	v_cvt_pk_bf16_f32 v0, v0, v1
	v_cvt_pk_bf16_f32 v1, v2, v3
	ds_write_b64 v110, v[0:1]
	v_add_u32_e32 v0, v87, v99
	ds_read_b128 v[0:3], v0
	s_waitcnt lgkmcnt(0)
	v_cvt_pk_bf16_f32 v0, v0, v1
	v_cvt_pk_bf16_f32 v1, v2, v3
	ds_write_b64 v111, v[0:1]
	v_add_u32_e32 v0, v90, v99
	ds_read_b128 v[0:3], v0
	s_waitcnt lgkmcnt(0)
	v_cvt_pk_bf16_f32 v0, v0, v1
	v_cvt_pk_bf16_f32 v1, v2, v3
	ds_write_b64 v112, v[0:1]
	v_add_u32_e32 v0, v93, v99
	ds_read_b128 v[0:3], v0
	s_waitcnt lgkmcnt(0)
	v_cvt_pk_bf16_f32 v0, v0, v1
	v_cvt_pk_bf16_f32 v1, v2, v3
	ds_write_b64 v113, v[0:1]
	s_waitcnt lgkmcnt(0)
	s_barrier
	global_load_dwordx4 v[198:201], v[56:57], off
	global_load_dwordx4 v[202:205], v[58:59], off
	global_load_dwordx4 v[206:209], v[56:57], off offset:64
	global_load_dwordx4 v[210:213], v[58:59], off offset:64
	global_load_dwordx4 v[214:217], v[56:57], off offset:128
	global_load_dwordx4 v[218:221], v[58:59], off offset:128
	global_load_dwordx4 v[222:225], v[56:57], off offset:192
	global_load_dwordx4 v[226:229], v[58:59], off offset:192
	global_load_dwordx4 v[230:233], v[56:57], off offset:256
	global_load_dwordx4 v[234:237], v[58:59], off offset:256
	global_load_dwordx4 v[238:241], v[56:57], off offset:320
	global_load_dwordx4 v[242:245], v[58:59], off offset:320
	global_load_dwordx4 v[246:249], v[56:57], off offset:384
	global_load_dwordx4 v[250:253], v[58:59], off offset:384
	global_load_dwordx4 v[126:129], v[56:57], off offset:448
	global_load_dwordx4 v[130:133], v[58:59], off offset:448
	ds_read_b128 v[8:11], v114
	ds_read_b128 v[12:15], v114 offset:8448
	ds_read_b128 v[16:19], v114 offset:16896
	ds_read_b128 v[20:23], v114 offset:25344
	s_waitcnt vmcnt(15) lgkmcnt(3)
	v_mfma_f32_16x16x32_bf16 v[24:27], v[8:11], v[198:201], 0
	s_waitcnt vmcnt(14)
	v_mfma_f32_16x16x32_bf16 v[8:11], v[8:11], v[202:205], 0
	s_waitcnt lgkmcnt(2)
	v_mfma_f32_16x16x32_bf16 v[28:31], v[12:15], v[198:201], 0
	v_mfma_f32_16x16x32_bf16 v[12:15], v[12:15], v[202:205], 0
	s_waitcnt lgkmcnt(1)
	v_mfma_f32_16x16x32_bf16 v[32:35], v[16:19], v[198:201], 0
	v_mfma_f32_16x16x32_bf16 v[16:19], v[16:19], v[202:205], 0
	s_waitcnt lgkmcnt(0)
	v_mfma_f32_16x16x32_bf16 v[0:3], v[20:23], v[198:201], 0
	v_mfma_f32_16x16x32_bf16 v[4:7], v[20:23], v[202:205], 0
	ds_read_b128 v[40:43], v114 offset:64
	ds_read_b128 v[44:47], v114 offset:8512
	ds_read_b128 v[48:51], v114 offset:16960
	ds_read_b128 v[66:69], v114 offset:25408
	s_waitcnt vmcnt(13) lgkmcnt(3)
	v_mfma_f32_16x16x32_bf16 v[24:27], v[40:43], v[206:209], v[24:27]
	s_waitcnt vmcnt(12)
	v_mfma_f32_16x16x32_bf16 v[8:11], v[40:43], v[210:213], v[8:11]
	s_waitcnt lgkmcnt(2)
	v_mfma_f32_16x16x32_bf16 v[28:31], v[44:47], v[206:209], v[28:31]
	v_mfma_f32_16x16x32_bf16 v[12:15], v[44:47], v[210:213], v[12:15]
	s_waitcnt lgkmcnt(1)
	v_mfma_f32_16x16x32_bf16 v[32:35], v[48:51], v[206:209], v[32:35]
	v_mfma_f32_16x16x32_bf16 v[16:19], v[48:51], v[210:213], v[16:19]
	s_waitcnt lgkmcnt(0)
	v_mfma_f32_16x16x32_bf16 v[0:3], v[66:69], v[206:209], v[0:3]
	v_mfma_f32_16x16x32_bf16 v[4:7], v[66:69], v[210:213], v[4:7]
	ds_read_b128 v[40:43], v114 offset:128
	ds_read_b128 v[44:47], v114 offset:8576
	ds_read_b128 v[48:51], v114 offset:17024
	ds_read_b128 v[66:69], v114 offset:25472
	s_waitcnt vmcnt(11) lgkmcnt(3)
	v_mfma_f32_16x16x32_bf16 v[24:27], v[40:43], v[214:217], v[24:27]
	s_waitcnt vmcnt(10)
	v_mfma_f32_16x16x32_bf16 v[8:11], v[40:43], v[218:221], v[8:11]
	s_waitcnt lgkmcnt(2)
	v_mfma_f32_16x16x32_bf16 v[28:31], v[44:47], v[214:217], v[28:31]
	v_mfma_f32_16x16x32_bf16 v[12:15], v[44:47], v[218:221], v[12:15]
	s_waitcnt lgkmcnt(1)
	v_mfma_f32_16x16x32_bf16 v[32:35], v[48:51], v[214:217], v[32:35]
	v_mfma_f32_16x16x32_bf16 v[16:19], v[48:51], v[218:221], v[16:19]
	s_waitcnt lgkmcnt(0)
	v_mfma_f32_16x16x32_bf16 v[0:3], v[66:69], v[214:217], v[0:3]
	v_mfma_f32_16x16x32_bf16 v[4:7], v[66:69], v[218:221], v[4:7]
	ds_read_b128 v[40:43], v114 offset:192
	ds_read_b128 v[44:47], v114 offset:8640
	ds_read_b128 v[48:51], v114 offset:17088
	ds_read_b128 v[66:69], v114 offset:25536
	s_waitcnt vmcnt(9) lgkmcnt(3)
	v_mfma_f32_16x16x32_bf16 v[24:27], v[40:43], v[222:225], v[24:27]
	s_waitcnt vmcnt(8)
	v_mfma_f32_16x16x32_bf16 v[8:11], v[40:43], v[226:229], v[8:11]
	s_waitcnt lgkmcnt(2)
	v_mfma_f32_16x16x32_bf16 v[28:31], v[44:47], v[222:225], v[28:31]
	v_mfma_f32_16x16x32_bf16 v[12:15], v[44:47], v[226:229], v[12:15]
	s_waitcnt lgkmcnt(1)
	v_mfma_f32_16x16x32_bf16 v[32:35], v[48:51], v[222:225], v[32:35]
	v_mfma_f32_16x16x32_bf16 v[16:19], v[48:51], v[226:229], v[16:19]
	s_waitcnt lgkmcnt(0)
	v_mfma_f32_16x16x32_bf16 v[0:3], v[66:69], v[222:225], v[0:3]
	v_mfma_f32_16x16x32_bf16 v[4:7], v[66:69], v[226:229], v[4:7]
	ds_read_b128 v[40:43], v114 offset:256
	ds_read_b128 v[44:47], v114 offset:8704
	ds_read_b128 v[48:51], v114 offset:17152
	ds_read_b128 v[66:69], v114 offset:25600
	s_waitcnt vmcnt(7) lgkmcnt(3)
	v_mfma_f32_16x16x32_bf16 v[24:27], v[40:43], v[230:233], v[24:27]
	s_waitcnt vmcnt(6)
	v_mfma_f32_16x16x32_bf16 v[8:11], v[40:43], v[234:237], v[8:11]
	s_waitcnt lgkmcnt(2)
	v_mfma_f32_16x16x32_bf16 v[28:31], v[44:47], v[230:233], v[28:31]
	v_mfma_f32_16x16x32_bf16 v[12:15], v[44:47], v[234:237], v[12:15]
	s_waitcnt lgkmcnt(1)
	v_mfma_f32_16x16x32_bf16 v[32:35], v[48:51], v[230:233], v[32:35]
	v_mfma_f32_16x16x32_bf16 v[16:19], v[48:51], v[234:237], v[16:19]
	s_waitcnt lgkmcnt(0)
	v_mfma_f32_16x16x32_bf16 v[0:3], v[66:69], v[230:233], v[0:3]
	v_mfma_f32_16x16x32_bf16 v[4:7], v[66:69], v[234:237], v[4:7]
	ds_read_b128 v[40:43], v114 offset:320
	ds_read_b128 v[44:47], v114 offset:8768
	ds_read_b128 v[48:51], v114 offset:17216
	ds_read_b128 v[66:69], v114 offset:25664
	s_waitcnt vmcnt(5) lgkmcnt(3)
	v_mfma_f32_16x16x32_bf16 v[24:27], v[40:43], v[238:241], v[24:27]
	s_waitcnt vmcnt(4)
	v_mfma_f32_16x16x32_bf16 v[8:11], v[40:43], v[242:245], v[8:11]
	s_waitcnt lgkmcnt(2)
	v_mfma_f32_16x16x32_bf16 v[28:31], v[44:47], v[238:241], v[28:31]
	v_mfma_f32_16x16x32_bf16 v[12:15], v[44:47], v[242:245], v[12:15]
	s_waitcnt lgkmcnt(1)
	v_mfma_f32_16x16x32_bf16 v[32:35], v[48:51], v[238:241], v[32:35]
	v_mfma_f32_16x16x32_bf16 v[16:19], v[48:51], v[242:245], v[16:19]
	s_waitcnt lgkmcnt(0)
	v_mfma_f32_16x16x32_bf16 v[0:3], v[66:69], v[238:241], v[0:3]
	v_mfma_f32_16x16x32_bf16 v[4:7], v[66:69], v[242:245], v[4:7]
	ds_read_b128 v[40:43], v114 offset:384
	ds_read_b128 v[44:47], v114 offset:8832
	ds_read_b128 v[48:51], v114 offset:17280
	ds_read_b128 v[66:69], v114 offset:25728
	s_waitcnt vmcnt(3) lgkmcnt(3)
	v_mfma_f32_16x16x32_bf16 v[24:27], v[40:43], v[246:249], v[24:27]
	s_waitcnt vmcnt(2)
	v_mfma_f32_16x16x32_bf16 v[8:11], v[40:43], v[250:253], v[8:11]
	s_waitcnt lgkmcnt(2)
	v_mfma_f32_16x16x32_bf16 v[40:43], v[44:47], v[246:249], v[28:31]
	v_mfma_f32_16x16x32_bf16 v[12:15], v[44:47], v[250:253], v[12:15]
	s_waitcnt lgkmcnt(1)
	v_mfma_f32_16x16x32_bf16 v[32:35], v[48:51], v[246:249], v[32:35]
	v_mfma_f32_16x16x32_bf16 v[44:47], v[48:51], v[250:253], v[16:19]
	s_waitcnt lgkmcnt(0)
	v_mfma_f32_16x16x32_bf16 v[36:39], v[66:69], v[250:253], v[4:7]
	s_nop 2
	v_mfma_f32_16x16x32_bf16 v[0:3], v[66:69], v[246:249], v[0:3]
	ds_read_b128 v[16:19], v114 offset:448
	ds_read_b128 v[66:69], v114 offset:8896
	ds_read_b128 v[118:121], v114 offset:17344
	ds_read_b128 v[122:125], v114 offset:25792
	s_waitcnt vmcnt(1) lgkmcnt(3)
	v_mfma_f32_16x16x32_bf16 v[28:31], v[16:19], v[126:129], v[24:27]
	s_nop 7
	v_mul_f32_e32 v28, 0xbfb8aa3b, v28
	v_exp_f32_e32 v28, v28
	s_waitcnt vmcnt(0)
	v_mfma_f32_16x16x32_bf16 v[24:27], v[16:19], v[130:133], v[8:11]
	v_mul_f32_e32 v30, 0xbfb8aa3b, v30
	v_exp_f32_e32 v30, v30
	v_add_f32_e32 v28, 1.0, v28
	s_waitcnt lgkmcnt(2)
	v_mfma_f32_16x16x32_bf16 v[16:19], v[66:69], v[130:133], v[12:15]
	v_mul_f32_e32 v31, 0xbfb8aa3b, v31
	v_add_f32_e32 v30, 1.0, v30
	v_exp_f32_e32 v31, v31
	s_waitcnt lgkmcnt(1)
	v_mfma_f32_16x16x32_bf16 v[12:15], v[118:121], v[126:129], v[32:35]
	v_mul_f32_e32 v24, 0xbfb8aa3b, v24
	v_exp_f32_e32 v24, v24
	v_add_f32_e32 v31, 1.0, v31
	v_div_scale_f32 v34, s[12:13], v28, v28, 1.0
	v_rcp_f32_e32 v35, v34
	v_mfma_f32_16x16x32_bf16 v[20:23], v[66:69], v[126:129], v[40:43]
	ds_read2_b32 v[32:33], v115 offset1:16
	v_add_f32_e32 v24, 1.0, v24
	v_mul_f32_e32 v16, 0xbfb8aa3b, v16
	s_waitcnt lgkmcnt(1)
	v_mfma_f32_16x16x32_bf16 v[4:7], v[122:125], v[126:129], v[0:3]
	v_exp_f32_e32 v16, v16
	s_nop 1
	v_mul_f32_e32 v20, 0xbfb8aa3b, v20
	v_exp_f32_e32 v20, v20
	v_mfma_f32_16x16x32_bf16 v[0:3], v[122:125], v[130:133], v[36:39]
	v_mul_f32_e32 v22, 0xbfb8aa3b, v22
	v_exp_f32_e32 v22, v22
	v_add_f32_e32 v20, 1.0, v20
	v_fma_f32 v36, -v34, v35, 1.0
	v_fmac_f32_e32 v35, v36, v35
	v_div_scale_f32 v36, vcc, 1.0, v28, 1.0
	v_mul_f32_e32 v37, v36, v35
	v_fma_f32 v38, -v34, v37, v36
	v_fmac_f32_e32 v37, v38, v35
	v_fma_f32 v34, -v34, v37, v36
	v_div_fmas_f32 v34, v34, v35, v37
	v_div_fixup_f32 v28, v34, v28, 1.0
	s_waitcnt lgkmcnt(0)
	v_mul_f32_e32 v32, v28, v32
	v_mul_f32_e32 v28, 0xbfb8aa3b, v29
	v_exp_f32_e32 v28, v28
	v_add_u32_e32 v38, 0x400, v115
	ds_read2_b32 v[34:35], v38 offset1:16
	v_mfma_f32_16x16x32_bf16 v[8:11], v[118:121], v[130:133], v[44:47]
	v_add_f32_e32 v28, 1.0, v28
	v_div_scale_f32 v29, s[12:13], v28, v28, 1.0
	v_rcp_f32_e32 v36, v29
	v_add_f32_e32 v22, 1.0, v22
	v_mul_f32_e32 v23, 0xbfb8aa3b, v23
	v_exp_f32_e32 v23, v23
	v_fma_f32 v37, -v29, v36, 1.0
	v_fmac_f32_e32 v36, v37, v36
	v_div_scale_f32 v37, vcc, 1.0, v28, 1.0
	v_mul_f32_e32 v39, v37, v36
	v_fma_f32 v40, -v29, v39, v37
	v_fmac_f32_e32 v39, v40, v36
	v_fma_f32 v29, -v29, v39, v37
	v_div_fmas_f32 v29, v29, v36, v39
	v_div_scale_f32 v36, s[12:13], v30, v30, 1.0
	v_rcp_f32_e32 v37, v36
	v_div_fixup_f32 v28, v29, v28, 1.0
	v_add_u32_e32 v39, 0x800, v115
	s_waitcnt lgkmcnt(0)
	v_mul_f32_e32 v34, v28, v34
	v_fma_f32 v40, -v36, v37, 1.0
	v_fmac_f32_e32 v37, v40, v37
	v_div_scale_f32 v40, vcc, 1.0, v30, 1.0
	v_mul_f32_e32 v41, v40, v37
	v_fma_f32 v42, -v36, v41, v40
	v_fmac_f32_e32 v41, v42, v37
	v_fma_f32 v36, -v36, v41, v40
	v_div_scale_f32 v40, s[12:13], v31, v31, 1.0
	v_div_fmas_f32 v36, v36, v37, v41
	v_rcp_f32_e32 v41, v40
	ds_read2_b32 v[28:29], v39 offset1:16
	v_div_fixup_f32 v30, v36, v30, 1.0
	v_add_f32_e32 v23, 1.0, v23
	v_fma_f32 v42, -v40, v41, 1.0
	v_fmac_f32_e32 v41, v42, v41
	v_div_scale_f32 v42, vcc, 1.0, v31, 1.0
	s_waitcnt lgkmcnt(0)
	v_mul_f32_e32 v28, v30, v28
	v_add_u32_e32 v30, 0xc00, v115
	v_mul_f32_e32 v43, v42, v41
	ds_read2_b32 v[36:37], v30 offset1:16
	v_fma_f32 v44, -v40, v43, v42
	v_fmac_f32_e32 v43, v44, v41
	v_fma_f32 v40, -v40, v43, v42
	v_div_fmas_f32 v40, v40, v41, v43
	v_div_fixup_f32 v31, v40, v31, 1.0
	s_waitcnt lgkmcnt(0)
	v_mul_f32_e32 v31, v31, v36
	v_div_scale_f32 v36, s[12:13], v24, v24, 1.0
	v_rcp_f32_e32 v40, v36
	v_add_f32_e32 v16, 1.0, v16
	v_mul_f32_e32 v12, 0xbfb8aa3b, v12
	v_exp_f32_e32 v12, v12
	v_fma_f32 v41, -v36, v40, 1.0
	v_fmac_f32_e32 v40, v41, v40
	v_div_scale_f32 v41, vcc, 1.0, v24, 1.0
	v_mul_f32_e32 v42, v41, v40
	v_fma_f32 v43, -v36, v42, v41
	v_fmac_f32_e32 v42, v43, v40
	v_fma_f32 v36, -v36, v42, v41
	v_div_fmas_f32 v36, v36, v40, v42
	v_div_fixup_f32 v24, v36, v24, 1.0
	v_mul_f32_e32 v24, v24, v33
	ds_write2_b32 v115, v32, v24 offset1:16
	v_mul_f32_e32 v24, 0xbfb8aa3b, v25
	v_exp_f32_e32 v24, v24
	v_add_f32_e32 v12, 1.0, v12
	v_mul_f32_e32 v14, 0xbfb8aa3b, v14
	v_exp_f32_e32 v14, v14
	v_add_f32_e32 v24, 1.0, v24
	v_div_scale_f32 v25, s[12:13], v24, v24, 1.0
	v_rcp_f32_e32 v32, v25
	v_add_f32_e32 v14, 1.0, v14
	v_mul_f32_e32 v15, 0xbfb8aa3b, v15
	v_exp_f32_e32 v15, v15
	v_fma_f32 v33, -v25, v32, 1.0
	v_fmac_f32_e32 v32, v33, v32
	v_div_scale_f32 v33, vcc, 1.0, v24, 1.0
	v_mul_f32_e32 v36, v33, v32
	v_fma_f32 v40, -v25, v36, v33
	v_fmac_f32_e32 v36, v40, v32
	v_fma_f32 v25, -v25, v36, v33
	v_div_fmas_f32 v25, v25, v32, v36
	v_div_fixup_f32 v24, v25, v24, 1.0
	v_mul_f32_e32 v24, v24, v35
	ds_write2_b32 v38, v34, v24 offset1:16
	v_mul_f32_e32 v24, 0xbfb8aa3b, v26
	v_exp_f32_e32 v24, v24
	v_add_f32_e32 v15, 1.0, v15
	v_mul_f32_e32 v8, 0xbfb8aa3b, v8
	v_exp_f32_e32 v8, v8
	v_add_f32_e32 v24, 1.0, v24
	v_div_scale_f32 v25, s[12:13], v24, v24, 1.0
	v_rcp_f32_e32 v26, v25
	v_add_f32_e32 v8, 1.0, v8
	v_mul_f32_e32 v4, 0xbfb8aa3b, v4
	v_exp_f32_e32 v4, v4
	v_fma_f32 v32, -v25, v26, 1.0
	v_fmac_f32_e32 v26, v32, v26
	v_div_scale_f32 v32, vcc, 1.0, v24, 1.0
	v_mul_f32_e32 v33, v32, v26
	v_fma_f32 v34, -v25, v33, v32
	v_fmac_f32_e32 v33, v34, v26
	v_fma_f32 v25, -v25, v33, v32
	v_div_fmas_f32 v25, v25, v26, v33
	v_div_fixup_f32 v24, v25, v24, 1.0
	v_mul_f32_e32 v24, v24, v29
	ds_write2_b32 v39, v28, v24 offset1:16
	v_mul_f32_e32 v24, 0xbfb8aa3b, v27
	v_exp_f32_e32 v24, v24
	v_add_f32_e32 v4, 1.0, v4
	v_mul_f32_e32 v6, 0xbfb8aa3b, v6
	v_exp_f32_e32 v6, v6
	v_add_f32_e32 v24, 1.0, v24
	v_div_scale_f32 v25, s[12:13], v24, v24, 1.0
	v_rcp_f32_e32 v26, v25
	v_add_f32_e32 v6, 1.0, v6
	v_mul_f32_e32 v7, 0xbfb8aa3b, v7
	v_exp_f32_e32 v7, v7
	v_fma_f32 v27, -v25, v26, 1.0
	v_fmac_f32_e32 v26, v27, v26
	v_div_scale_f32 v27, vcc, 1.0, v24, 1.0
	v_mul_f32_e32 v28, v27, v26
	v_fma_f32 v29, -v25, v28, v27
	v_fmac_f32_e32 v28, v29, v26
	v_fma_f32 v25, -v25, v28, v27
	v_div_fmas_f32 v25, v25, v26, v28
	v_div_scale_f32 v26, s[12:13], v20, v20, 1.0
	v_rcp_f32_e32 v27, v26
	v_div_fixup_f32 v24, v25, v24, 1.0
	v_mul_f32_e32 v24, v24, v37
	ds_write2_b32 v30, v31, v24 offset1:16
	v_fma_f32 v28, -v26, v27, 1.0
	v_fmac_f32_e32 v27, v28, v27
	v_div_scale_f32 v28, vcc, 1.0, v20, 1.0
	v_add_u32_e32 v30, 0x4000, v115
	v_mul_f32_e32 v29, v28, v27
	ds_read2_b32 v[24:25], v30 offset1:16
	v_fma_f32 v31, -v26, v29, v28
	v_fmac_f32_e32 v29, v31, v27
	v_fma_f32 v26, -v26, v29, v28
	v_div_fmas_f32 v26, v26, v27, v29
	v_div_fixup_f32 v20, v26, v20, 1.0
	s_waitcnt lgkmcnt(0)
	v_mul_f32_e32 v24, v20, v24
	v_mul_f32_e32 v20, 0xbfb8aa3b, v21
	v_exp_f32_e32 v20, v20
	v_add_u32_e32 v31, 0x4400, v115
	ds_read2_b32 v[26:27], v31 offset1:16
	v_add_f32_e32 v7, 1.0, v7
	v_add_f32_e32 v20, 1.0, v20
	v_div_scale_f32 v21, s[12:13], v20, v20, 1.0
	v_rcp_f32_e32 v28, v21
	v_mul_f32_e32 v0, 0xbfb8aa3b, v0
	v_exp_f32_e32 v0, v0
	v_fma_f32 v29, -v21, v28, 1.0
	v_fmac_f32_e32 v28, v29, v28
	v_div_scale_f32 v29, vcc, 1.0, v20, 1.0
	v_mul_f32_e32 v32, v29, v28
	v_fma_f32 v33, -v21, v32, v29
	v_fmac_f32_e32 v32, v33, v28
	v_fma_f32 v21, -v21, v32, v29
	v_div_fmas_f32 v21, v21, v28, v32
	v_div_scale_f32 v28, s[12:13], v22, v22, 1.0
	v_rcp_f32_e32 v29, v28
	v_div_fixup_f32 v20, v21, v20, 1.0
	v_add_u32_e32 v32, 0x4800, v115
	s_waitcnt lgkmcnt(0)
	v_mul_f32_e32 v26, v20, v26
	v_fma_f32 v33, -v28, v29, 1.0
	v_fmac_f32_e32 v29, v33, v29
	v_div_scale_f32 v33, vcc, 1.0, v22, 1.0
	v_mul_f32_e32 v34, v33, v29
	v_fma_f32 v35, -v28, v34, v33
	v_fmac_f32_e32 v34, v35, v29
	v_fma_f32 v28, -v28, v34, v33
	v_div_scale_f32 v33, s[12:13], v23, v23, 1.0
	v_div_fmas_f32 v28, v28, v29, v34
	v_rcp_f32_e32 v34, v33
	ds_read2_b32 v[20:21], v32 offset1:16
	v_div_fixup_f32 v22, v28, v22, 1.0
	v_add_f32_e32 v0, 1.0, v0
	v_fma_f32 v35, -v33, v34, 1.0
	v_fmac_f32_e32 v34, v35, v34
	v_div_scale_f32 v35, vcc, 1.0, v23, 1.0
	s_waitcnt lgkmcnt(0)
	v_mul_f32_e32 v20, v22, v20
	v_add_u32_e32 v22, 0x4c00, v115
	v_mul_f32_e32 v36, v35, v34
	ds_read2_b32 v[28:29], v22 offset1:16
	v_fma_f32 v37, -v33, v36, v35
	v_fmac_f32_e32 v36, v37, v34
	v_fma_f32 v33, -v33, v36, v35
	v_div_fmas_f32 v33, v33, v34, v36
	v_div_fixup_f32 v23, v33, v23, 1.0
	s_waitcnt lgkmcnt(0)
	v_mul_f32_e32 v23, v23, v28
	v_div_scale_f32 v28, s[12:13], v16, v16, 1.0
	v_rcp_f32_e32 v33, v28
	s_nop 0
	v_fma_f32 v34, -v28, v33, 1.0
	v_fmac_f32_e32 v33, v34, v33
	v_div_scale_f32 v34, vcc, 1.0, v16, 1.0
	v_mul_f32_e32 v35, v34, v33
	v_fma_f32 v36, -v28, v35, v34
	v_fmac_f32_e32 v35, v36, v33
	v_fma_f32 v28, -v28, v35, v34
	v_div_fmas_f32 v28, v28, v33, v35
	v_div_fixup_f32 v16, v28, v16, 1.0
	v_mul_f32_e32 v16, v16, v25
	ds_write2_b32 v30, v24, v16 offset1:16
	v_mul_f32_e32 v16, 0xbfb8aa3b, v17
	v_exp_f32_e32 v16, v16
	s_nop 0
	v_add_f32_e32 v16, 1.0, v16
	v_div_scale_f32 v17, s[12:13], v16, v16, 1.0
	v_rcp_f32_e32 v24, v17
	s_nop 0
	v_fma_f32 v25, -v17, v24, 1.0
	v_fmac_f32_e32 v24, v25, v24
	v_div_scale_f32 v25, vcc, 1.0, v16, 1.0
	v_mul_f32_e32 v28, v25, v24
	v_fma_f32 v30, -v17, v28, v25
	v_fmac_f32_e32 v28, v30, v24
	v_fma_f32 v17, -v17, v28, v25
	v_div_fmas_f32 v17, v17, v24, v28
	v_div_fixup_f32 v16, v17, v16, 1.0
	v_mul_f32_e32 v16, v16, v27
	ds_write2_b32 v31, v26, v16 offset1:16
	v_mul_f32_e32 v16, 0xbfb8aa3b, v18
	v_exp_f32_e32 v16, v16
	s_nop 0
	v_add_f32_e32 v16, 1.0, v16
	v_div_scale_f32 v17, s[12:13], v16, v16, 1.0
	v_rcp_f32_e32 v18, v17
	s_nop 0
	v_fma_f32 v24, -v17, v18, 1.0
	v_fmac_f32_e32 v18, v24, v18
	v_div_scale_f32 v24, vcc, 1.0, v16, 1.0
	v_mul_f32_e32 v25, v24, v18
	v_fma_f32 v26, -v17, v25, v24
	v_fmac_f32_e32 v25, v26, v18
	v_fma_f32 v17, -v17, v25, v24
	v_div_fmas_f32 v17, v17, v18, v25
	v_div_fixup_f32 v16, v17, v16, 1.0
	v_mul_f32_e32 v16, v16, v21
	ds_write2_b32 v32, v20, v16 offset1:16
	v_mul_f32_e32 v16, 0xbfb8aa3b, v19
	v_exp_f32_e32 v16, v16
	s_nop 0
	v_add_f32_e32 v16, 1.0, v16
	v_div_scale_f32 v17, s[12:13], v16, v16, 1.0
	v_rcp_f32_e32 v18, v17
	s_nop 0
	v_fma_f32 v19, -v17, v18, 1.0
	v_fmac_f32_e32 v18, v19, v18
	v_div_scale_f32 v19, vcc, 1.0, v16, 1.0
	v_mul_f32_e32 v20, v19, v18
	v_fma_f32 v21, -v17, v20, v19
	v_fmac_f32_e32 v20, v21, v18
	v_fma_f32 v17, -v17, v20, v19
	v_div_fmas_f32 v17, v17, v18, v20
	v_div_scale_f32 v18, s[12:13], v12, v12, 1.0
	v_rcp_f32_e32 v19, v18
	v_div_fixup_f32 v16, v17, v16, 1.0
	v_mul_f32_e32 v16, v16, v29
	ds_write2_b32 v22, v23, v16 offset1:16
	v_fma_f32 v20, -v18, v19, 1.0
	v_fmac_f32_e32 v19, v20, v19
	v_div_scale_f32 v20, vcc, 1.0, v12, 1.0
	v_add_u32_e32 v22, 0x8000, v115
	v_mul_f32_e32 v21, v20, v19
	ds_read2_b32 v[16:17], v22 offset1:16
	v_fma_f32 v23, -v18, v21, v20
	v_fmac_f32_e32 v21, v23, v19
	v_fma_f32 v18, -v18, v21, v20
	v_div_fmas_f32 v18, v18, v19, v21
	v_div_fixup_f32 v12, v18, v12, 1.0
	s_waitcnt lgkmcnt(0)
	v_mul_f32_e32 v16, v12, v16
	v_mul_f32_e32 v12, 0xbfb8aa3b, v13
	v_exp_f32_e32 v12, v12
	v_add_u32_e32 v23, 0x8400, v115
	ds_read2_b32 v[18:19], v23 offset1:16
	v_add_f32_e32 v12, 1.0, v12
	v_div_scale_f32 v13, s[12:13], v12, v12, 1.0
	v_rcp_f32_e32 v20, v13
	s_nop 0
	v_fma_f32 v21, -v13, v20, 1.0
	v_fmac_f32_e32 v20, v21, v20
	v_div_scale_f32 v21, vcc, 1.0, v12, 1.0
	v_mul_f32_e32 v24, v21, v20
	v_fma_f32 v25, -v13, v24, v21
	v_fmac_f32_e32 v24, v25, v20
	v_fma_f32 v13, -v13, v24, v21
	v_div_fmas_f32 v13, v13, v20, v24
	v_div_scale_f32 v20, s[12:13], v14, v14, 1.0
	v_rcp_f32_e32 v21, v20
	v_div_fixup_f32 v12, v13, v12, 1.0
	v_add_u32_e32 v24, 0x8800, v115
	s_waitcnt lgkmcnt(0)
	v_mul_f32_e32 v18, v12, v18
	v_fma_f32 v25, -v20, v21, 1.0
	v_fmac_f32_e32 v21, v25, v21
	v_div_scale_f32 v25, vcc, 1.0, v14, 1.0
	v_mul_f32_e32 v26, v25, v21
	v_fma_f32 v27, -v20, v26, v25
	v_fmac_f32_e32 v26, v27, v21
	v_fma_f32 v20, -v20, v26, v25
	v_div_scale_f32 v25, s[12:13], v15, v15, 1.0
	v_div_fmas_f32 v20, v20, v21, v26
	v_rcp_f32_e32 v26, v25
	ds_read2_b32 v[12:13], v24 offset1:16
	v_div_fixup_f32 v14, v20, v14, 1.0
	v_fma_f32 v27, -v25, v26, 1.0
	v_fmac_f32_e32 v26, v27, v26
	v_div_scale_f32 v27, vcc, 1.0, v15, 1.0
	s_waitcnt lgkmcnt(0)
	v_mul_f32_e32 v12, v14, v12
	v_add_u32_e32 v14, 0x8c00, v115
	v_mul_f32_e32 v28, v27, v26
	ds_read2_b32 v[20:21], v14 offset1:16
	v_fma_f32 v29, -v25, v28, v27
	v_fmac_f32_e32 v28, v29, v26
	v_fma_f32 v25, -v25, v28, v27
	v_div_fmas_f32 v25, v25, v26, v28
	v_div_fixup_f32 v15, v25, v15, 1.0
	s_waitcnt lgkmcnt(0)
	v_mul_f32_e32 v15, v15, v20
	v_div_scale_f32 v20, s[12:13], v8, v8, 1.0
	v_rcp_f32_e32 v25, v20
	s_nop 0
	v_fma_f32 v26, -v20, v25, 1.0
	v_fmac_f32_e32 v25, v26, v25
	v_div_scale_f32 v26, vcc, 1.0, v8, 1.0
	v_mul_f32_e32 v27, v26, v25
	v_fma_f32 v28, -v20, v27, v26
	v_fmac_f32_e32 v27, v28, v25
	v_fma_f32 v20, -v20, v27, v26
	v_div_fmas_f32 v20, v20, v25, v27
	v_div_fixup_f32 v8, v20, v8, 1.0
	v_mul_f32_e32 v8, v8, v17
	ds_write2_b32 v22, v16, v8 offset1:16
	v_mul_f32_e32 v8, 0xbfb8aa3b, v9
	v_exp_f32_e32 v8, v8
	s_nop 0
	v_add_f32_e32 v8, 1.0, v8
	v_div_scale_f32 v9, s[12:13], v8, v8, 1.0
	v_rcp_f32_e32 v16, v9
	s_nop 0
	v_fma_f32 v17, -v9, v16, 1.0
	v_fmac_f32_e32 v16, v17, v16
	v_div_scale_f32 v17, vcc, 1.0, v8, 1.0
	v_mul_f32_e32 v20, v17, v16
	v_fma_f32 v22, -v9, v20, v17
	v_fmac_f32_e32 v20, v22, v16
	v_fma_f32 v9, -v9, v20, v17
	v_div_fmas_f32 v9, v9, v16, v20
	v_div_fixup_f32 v8, v9, v8, 1.0
	v_mul_f32_e32 v8, v8, v19
	ds_write2_b32 v23, v18, v8 offset1:16
	v_mul_f32_e32 v8, 0xbfb8aa3b, v10
	v_exp_f32_e32 v8, v8
	s_nop 0
	v_add_f32_e32 v8, 1.0, v8
	v_div_scale_f32 v9, s[12:13], v8, v8, 1.0
	v_rcp_f32_e32 v10, v9
	s_nop 0
	v_fma_f32 v16, -v9, v10, 1.0
	v_fmac_f32_e32 v10, v16, v10
	v_div_scale_f32 v16, vcc, 1.0, v8, 1.0
	v_mul_f32_e32 v17, v16, v10
	v_fma_f32 v18, -v9, v17, v16
	v_fmac_f32_e32 v17, v18, v10
	v_fma_f32 v9, -v9, v17, v16
	v_div_fmas_f32 v9, v9, v10, v17
	v_div_fixup_f32 v8, v9, v8, 1.0
	v_mul_f32_e32 v8, v8, v13
	ds_write2_b32 v24, v12, v8 offset1:16
	v_mul_f32_e32 v8, 0xbfb8aa3b, v11
	v_exp_f32_e32 v8, v8
	s_nop 0
	v_add_f32_e32 v8, 1.0, v8
	v_div_scale_f32 v9, s[12:13], v8, v8, 1.0
	v_rcp_f32_e32 v10, v9
	s_nop 0
	v_fma_f32 v11, -v9, v10, 1.0
	v_fmac_f32_e32 v10, v11, v10
	v_div_scale_f32 v11, vcc, 1.0, v8, 1.0
	v_mul_f32_e32 v12, v11, v10
	v_fma_f32 v13, -v9, v12, v11
	v_fmac_f32_e32 v12, v13, v10
	v_fma_f32 v9, -v9, v12, v11
	v_div_fmas_f32 v9, v9, v10, v12
	v_div_scale_f32 v10, s[12:13], v4, v4, 1.0
	v_rcp_f32_e32 v11, v10
	v_div_fixup_f32 v8, v9, v8, 1.0
	v_mul_f32_e32 v8, v8, v21
	ds_write2_b32 v14, v15, v8 offset1:16
	v_fma_f32 v12, -v10, v11, 1.0
	v_fmac_f32_e32 v11, v12, v11
	v_div_scale_f32 v12, vcc, 1.0, v4, 1.0
	v_add_u32_e32 v14, 0xc000, v115
	v_mul_f32_e32 v13, v12, v11
	ds_read2_b32 v[8:9], v14 offset1:16
	v_fma_f32 v15, -v10, v13, v12
	v_fmac_f32_e32 v13, v15, v11
	v_fma_f32 v10, -v10, v13, v12
	v_div_fmas_f32 v10, v10, v11, v13
	v_div_fixup_f32 v4, v10, v4, 1.0
	s_waitcnt lgkmcnt(0)
	v_mul_f32_e32 v8, v4, v8
	v_mul_f32_e32 v4, 0xbfb8aa3b, v5
	v_exp_f32_e32 v4, v4
	v_add_u32_e32 v15, 0xc400, v115
	ds_read2_b32 v[10:11], v15 offset1:16
	v_add_f32_e32 v4, 1.0, v4
	v_div_scale_f32 v5, s[12:13], v4, v4, 1.0
	v_rcp_f32_e32 v12, v5
	s_nop 0
	v_fma_f32 v13, -v5, v12, 1.0
	v_fmac_f32_e32 v12, v13, v12
	v_div_scale_f32 v13, vcc, 1.0, v4, 1.0
	v_mul_f32_e32 v16, v13, v12
	v_fma_f32 v17, -v5, v16, v13
	v_fmac_f32_e32 v16, v17, v12
	v_fma_f32 v5, -v5, v16, v13
	v_div_fmas_f32 v5, v5, v12, v16
	v_div_scale_f32 v12, s[12:13], v6, v6, 1.0
	v_rcp_f32_e32 v13, v12
	v_div_fixup_f32 v4, v5, v4, 1.0
	v_add_u32_e32 v16, 0xc800, v115
	s_waitcnt lgkmcnt(0)
	v_mul_f32_e32 v10, v4, v10
	v_fma_f32 v17, -v12, v13, 1.0
	v_fmac_f32_e32 v13, v17, v13
	v_div_scale_f32 v17, vcc, 1.0, v6, 1.0
	v_mul_f32_e32 v18, v17, v13
	v_fma_f32 v19, -v12, v18, v17
	v_fmac_f32_e32 v18, v19, v13
	v_fma_f32 v12, -v12, v18, v17
	v_div_scale_f32 v17, s[12:13], v7, v7, 1.0
	v_div_fmas_f32 v12, v12, v13, v18
	v_rcp_f32_e32 v18, v17
	ds_read2_b32 v[4:5], v16 offset1:16
	v_div_fixup_f32 v6, v12, v6, 1.0
	v_fma_f32 v19, -v17, v18, 1.0
	v_fmac_f32_e32 v18, v19, v18
	v_div_scale_f32 v19, vcc, 1.0, v7, 1.0
	s_waitcnt lgkmcnt(0)
	v_mul_f32_e32 v4, v6, v4
	v_add_u32_e32 v6, 0xcc00, v115
	v_mul_f32_e32 v20, v19, v18
	ds_read2_b32 v[12:13], v6 offset1:16
	v_fma_f32 v21, -v17, v20, v19
	v_fmac_f32_e32 v20, v21, v18
	v_fma_f32 v17, -v17, v20, v19
	v_div_fmas_f32 v17, v17, v18, v20
	v_div_fixup_f32 v7, v17, v7, 1.0
	s_waitcnt lgkmcnt(0)
	v_mul_f32_e32 v7, v7, v12
	v_div_scale_f32 v12, s[12:13], v0, v0, 1.0
	v_rcp_f32_e32 v17, v12
	s_nop 0
	v_fma_f32 v18, -v12, v17, 1.0
	v_fmac_f32_e32 v17, v18, v17
	v_div_scale_f32 v18, vcc, 1.0, v0, 1.0
	v_mul_f32_e32 v19, v18, v17
	v_fma_f32 v20, -v12, v19, v18
	v_fmac_f32_e32 v19, v20, v17
	v_fma_f32 v12, -v12, v19, v18
	v_div_fmas_f32 v12, v12, v17, v19
	v_div_fixup_f32 v0, v12, v0, 1.0
	v_mul_f32_e32 v0, v0, v9
	ds_write2_b32 v14, v8, v0 offset1:16
	v_mul_f32_e32 v0, 0xbfb8aa3b, v1
	v_exp_f32_e32 v0, v0
	s_nop 0
	v_add_f32_e32 v0, 1.0, v0
	v_div_scale_f32 v1, s[12:13], v0, v0, 1.0
	v_rcp_f32_e32 v8, v1
	s_nop 0
	v_fma_f32 v9, -v1, v8, 1.0
	v_fmac_f32_e32 v8, v9, v8
	v_div_scale_f32 v9, vcc, 1.0, v0, 1.0
	v_mul_f32_e32 v12, v9, v8
	v_fma_f32 v14, -v1, v12, v9
	v_fmac_f32_e32 v12, v14, v8
	v_fma_f32 v1, -v1, v12, v9
	v_div_fmas_f32 v1, v1, v8, v12
	v_div_fixup_f32 v0, v1, v0, 1.0
	v_mul_f32_e32 v0, v0, v11
	ds_write2_b32 v15, v10, v0 offset1:16
	v_mul_f32_e32 v0, 0xbfb8aa3b, v2
	v_exp_f32_e32 v0, v0
	s_nop 0
	v_add_f32_e32 v0, 1.0, v0
	v_div_scale_f32 v1, s[12:13], v0, v0, 1.0
	v_rcp_f32_e32 v2, v1
	s_nop 0
	v_fma_f32 v8, -v1, v2, 1.0
	v_fmac_f32_e32 v2, v8, v2
	v_div_scale_f32 v8, vcc, 1.0, v0, 1.0
	v_mul_f32_e32 v9, v8, v2
	v_fma_f32 v10, -v1, v9, v8
	v_fmac_f32_e32 v9, v10, v2
	v_fma_f32 v1, -v1, v9, v8
	v_div_fmas_f32 v1, v1, v2, v9
	v_div_fixup_f32 v0, v1, v0, 1.0
	v_mul_f32_e32 v0, v0, v5
	ds_write2_b32 v16, v4, v0 offset1:16
	v_mul_f32_e32 v0, 0xbfb8aa3b, v3
	v_exp_f32_e32 v0, v0
	s_nop 0
	v_add_f32_e32 v0, 1.0, v0
	v_div_scale_f32 v1, s[12:13], v0, v0, 1.0
	v_rcp_f32_e32 v2, v1
	s_nop 0
	v_fma_f32 v3, -v1, v2, 1.0
	v_fmac_f32_e32 v2, v3, v2
	v_div_scale_f32 v3, vcc, 1.0, v0, 1.0
	v_mul_f32_e32 v4, v3, v2
	v_fma_f32 v5, -v1, v4, v3
	v_fmac_f32_e32 v4, v5, v2
	v_fma_f32 v1, -v1, v4, v3
	v_div_fmas_f32 v1, v1, v2, v4
	v_div_fixup_f32 v0, v1, v0, 1.0
	v_mul_f32_e32 v0, v0, v13
	ds_write2_b32 v6, v7, v0 offset1:16
	s_waitcnt lgkmcnt(0)
	s_barrier
	ds_read_b128 v[24:27], v116
	ds_read_b128 v[20:23], v116 offset:16
	ds_read_b128 v[4:7], v116 offset:32
	ds_read_b128 v[0:3], v116 offset:48
	ds_read_b128 v[28:31], v116 offset:80
	s_waitcnt lgkmcnt(4)
	v_mov_b32_e32 v10, v25
	s_waitcnt lgkmcnt(3)
	v_mov_b32_e32 v11, v21
	v_mov_b32_e32 v8, v24
	v_mov_b32_e32 v9, v20
	v_pk_mul_f32 v[10:11], v[10:11], v[10:11]
	v_mov_b32_e32 v12, v27
	v_mov_b32_e32 v13, v23
	v_pk_fma_f32 v[8:9], v[8:9], v[8:9], v[10:11]
	v_mov_b32_e32 v10, v26
	v_mov_b32_e32 v11, v22
	v_pk_mul_f32 v[12:13], v[12:13], v[12:13]
	s_nop 0
	v_pk_fma_f32 v[10:11], v[10:11], v[10:11], v[12:13]
	s_nop 0
	v_pk_add_f32 v[12:13], v[8:9], v[10:11]
	s_waitcnt lgkmcnt(2)
	v_pk_mul_f32 v[8:9], v[6:7], v[6:7]
	v_pk_mul_f32 v[10:11], v[4:5], v[4:5]
	v_pk_add_f32 v[12:13], v[12:13], v[12:13] op_sel:[0,1] op_sel_hi:[1,0]
	v_pk_mov_b32 v[14:15], v[10:11], v[8:9] op_sel:[1,0]
	v_mov_b32_e32 v11, v9
	v_pk_add_f32 v[14:15], v[14:15], v[10:11]
	ds_read_b128 v[8:11], v116 offset:64
	v_pk_add_f32 v[14:15], v[14:15], v[14:15] op_sel:[0,1] op_sel_hi:[1,0]
	s_waitcnt lgkmcnt(0)
	v_mul_f32_e32 v16, v8, v8
	v_mul_f32_e32 v17, v9, v9
	v_mov_b32_e32 v13, v16
	v_mov_b32_e32 v15, v17
	v_pk_add_f32 v[12:13], v[12:13], v[14:15]
	v_mul_f32_e32 v14, v1, v1
	v_mul_f32_e32 v16, v3, v3
	v_mul_f32_e32 v18, v10, v10
	v_mul_f32_e32 v19, v11, v11
	v_pk_fma_f32 v[14:15], v[0:1], v[0:1], v[14:15] op_sel_hi:[1,1,0]
	v_pk_fma_f32 v[16:17], v[2:3], v[2:3], v[16:17] op_sel_hi:[1,1,0]
	v_mov_b32_e32 v15, v18
	v_mov_b32_e32 v17, v19
	v_pk_add_f32 v[14:15], v[14:15], v[16:17]
	s_nop 0
	v_pk_add_f32 v[32:33], v[12:13], v[14:15]
	v_pk_mul_f32 v[12:13], v[30:31], v[30:31]
	v_pk_mul_f32 v[14:15], v[28:29], v[28:29]
	v_pk_add_f32 v[32:33], v[32:33], v[32:33] op_sel:[0,1] op_sel_hi:[1,0]
	v_pk_mov_b32 v[16:17], v[14:15], v[12:13] op_sel:[1,0]
	v_mov_b32_e32 v15, v13
	v_pk_add_f32 v[34:35], v[16:17], v[14:15]
	ds_read_b128 v[16:19], v116 offset:96
	ds_read_b128 v[12:15], v116 offset:112
	v_pk_add_f32 v[34:35], v[34:35], v[34:35] op_sel:[0,1] op_sel_hi:[1,0]
	s_waitcnt lgkmcnt(0)
	v_mul_f32_e32 v36, v12, v12
	v_mul_f32_e32 v37, v13, v13
	v_mov_b32_e32 v33, v36
	v_mov_b32_e32 v35, v37
	v_pk_add_f32 v[32:33], v[32:33], v[34:35]
	v_mul_f32_e32 v34, v17, v17
	v_mul_f32_e32 v36, v19, v19
	v_mul_f32_e32 v38, v14, v14
	v_mul_f32_e32 v39, v15, v15
	v_pk_fma_f32 v[34:35], v[16:17], v[16:17], v[34:35] op_sel_hi:[1,1,0]
	v_pk_fma_f32 v[36:37], v[18:19], v[18:19], v[36:37] op_sel_hi:[1,1,0]
	v_mov_b32_e32 v35, v38
	v_mov_b32_e32 v37, v39
	v_pk_add_f32 v[34:35], v[34:35], v[36:37]
	s_nop 0
	v_pk_add_f32 v[32:33], v[32:33], v[34:35]
	s_nop 0
	v_add_f32_e32 v32, v32, v33
	s_nop 1
	v_add_f32_dpp v32, v32, v32 quad_perm:[1,0,3,2] row_mask:0xf bank_mask:0xf bound_ctrl:1
	s_nop 1
	v_add_f32_dpp v32, v32, v32 quad_perm:[2,3,0,1] row_mask:0xf bank_mask:0xf bound_ctrl:1
	s_nop 1
	v_add_f32_dpp v32, v32, v32 row_half_mirror row_mask:0xf bank_mask:0xf bound_ctrl:1
	v_fmamk_f32 v32, v32, 0x3b800000, v182
	v_cmp_gt_f32_e32 vcc, s50, v32
	v_mul_f32_e32 v33, 0x4f800000, v32
	s_nop 0
	v_cndmask_b32_e32 v32, v32, v33, vcc
	v_sqrt_f32_e32 v33, v32
	s_nop 0
	v_add_u32_e32 v34, -1, v33
	v_fma_f32 v35, -v34, v33, v32
	v_cmp_ge_f32_e64 s[12:13], 0, v35
	v_add_u32_e32 v35, 1, v33
	s_nop 0
	v_cndmask_b32_e64 v34, v33, v34, s[12:13]
	v_fma_f32 v33, -v35, v33, v32
	v_cmp_lt_f32_e64 s[12:13], 0, v33
	s_nop 1
	v_cndmask_b32_e64 v33, v34, v35, s[12:13]
	v_mul_f32_e32 v34, 0x37800000, v33
	v_cndmask_b32_e32 v33, v33, v34, vcc
	v_cmp_class_f32_e32 vcc, v32, v183
	s_nop 1
	v_cndmask_b32_e32 v32, v33, v32, vcc
	v_div_scale_f32 v33, s[12:13], v32, v32, 1.0
	v_rcp_f32_e32 v34, v33
	s_mov_b64 s[12:13], 0x5000200
	v_fma_f32 v35, -v33, v34, 1.0
	v_fmac_f32_e32 v34, v35, v34
	v_div_scale_f32 v35, vcc, 1.0, v32, 1.0
	v_mul_f32_e32 v36, v35, v34
	v_fma_f32 v37, -v33, v36, v35
	v_fmac_f32_e32 v36, v37, v34
	v_fma_f32 v33, -v33, v36, v35
	v_div_fmas_f32 v33, v33, v34, v36
	v_div_fixup_f32 v40, v33, v32, 1.0
	v_add_u32_e32 v32, s52, v100
	v_ashrrev_i32_e32 v33, 31, v32
	v_lshlrev_b64 v[32:33], 11, v[32:33]
	v_lshl_add_u64 v[32:33], s[18:19], 0, v[32:33]
	v_lshl_add_u64 v[44:45], v[32:33], 0, v[64:65]
	global_load_dwordx4 v[32:35], v[60:61], off offset:16
	global_load_dwordx4 v[36:39], v[60:61], off
	v_pk_mul_f32 v[24:25], v[24:25], v[40:41] op_sel_hi:[1,0]
	v_pk_mul_f32 v[26:27], v[26:27], v[40:41] op_sel_hi:[1,0]
	v_pk_mul_f32 v[20:21], v[20:21], v[40:41] op_sel_hi:[1,0]
	v_pk_mul_f32 v[4:5], v[4:5], v[40:41] op_sel_hi:[1,0]
	v_pk_mul_f32 v[6:7], v[6:7], v[40:41] op_sel_hi:[1,0]
	v_pk_mul_f32 v[0:1], v[0:1], v[40:41] op_sel_hi:[1,0]
	v_lshl_add_u64 v[42:43], v[44:45], 0, s[12:13]
	v_pk_mul_f32 v[8:9], v[8:9], v[40:41] op_sel_hi:[1,0]
	s_waitcnt vmcnt(1)
	v_pk_mul_f32 v[20:21], v[32:33], v[20:21]
	s_waitcnt vmcnt(0)
	v_pk_mul_f32 v[24:25], v[36:37], v[24:25]
	v_pk_mul_f32 v[26:27], v[38:39], v[26:27]
	v_cvt_pk_bf16_f32 v24, v24, v25
	v_cvt_pk_bf16_f32 v25, v26, v27
	v_cvt_pk_bf16_f32 v26, v20, v21
	v_pk_mul_f32 v[20:21], v[22:23], v[40:41] op_sel_hi:[1,0]
	s_nop 0
	v_pk_mul_f32 v[20:21], v[34:35], v[20:21]
	s_nop 0
	v_cvt_pk_bf16_f32 v27, v20, v21
	v_add_co_u32_e32 v20, vcc, s1, v44
	s_nop 1
	v_addc_co_u32_e32 v21, vcc, 0, v45, vcc
	global_store_dwordx4 v[20:21], v[24:27], off offset:512
	global_load_dwordx4 v[20:23], v[60:61], off offset:48
	s_nop 0
	global_load_dwordx4 v[24:27], v[60:61], off offset:32
	s_waitcnt vmcnt(1)
	v_pk_mul_f32 v[0:1], v[0:1], v[20:21]
	s_waitcnt vmcnt(0)
	v_pk_mul_f32 v[4:5], v[4:5], v[24:25]
	v_pk_mul_f32 v[6:7], v[6:7], v[26:27]
	v_cvt_pk_bf16_f32 v4, v4, v5
	v_cvt_pk_bf16_f32 v5, v6, v7
	v_cvt_pk_bf16_f32 v6, v0, v1
	v_pk_mul_f32 v[0:1], v[2:3], v[40:41] op_sel_hi:[1,0]
	s_nop 0
	v_pk_mul_f32 v[0:1], v[0:1], v[22:23]
	s_nop 0
	v_cvt_pk_bf16_f32 v7, v0, v1
	global_store_dwordx4 v[42:43], v[4:7], off offset:16
	global_load_dwordx4 v[0:3], v[60:61], off offset:80
	s_nop 0
	global_load_dwordx4 v[4:7], v[60:61], off offset:64
	s_waitcnt vmcnt(0)
	v_pk_mul_f32 v[4:5], v[8:9], v[4:5]
	v_pk_mul_f32 v[8:9], v[10:11], v[40:41] op_sel_hi:[1,0]
	v_cvt_pk_bf16_f32 v4, v4, v5
	v_pk_mul_f32 v[6:7], v[8:9], v[6:7]
	v_pk_mul_f32 v[8:9], v[16:17], v[40:41] op_sel_hi:[1,0]
	v_cvt_pk_bf16_f32 v5, v6, v7
	v_pk_mul_f32 v[6:7], v[28:29], v[40:41] op_sel_hi:[1,0]
	s_nop 0
	v_pk_mul_f32 v[0:1], v[6:7], v[0:1]
	s_nop 0
	v_cvt_pk_bf16_f32 v6, v0, v1
	v_pk_mul_f32 v[0:1], v[30:31], v[40:41] op_sel_hi:[1,0]
	s_nop 0
	v_pk_mul_f32 v[0:1], v[0:1], v[2:3]
	s_nop 0
	v_cvt_pk_bf16_f32 v7, v0, v1
	global_store_dwordx4 v[42:43], v[4:7], off offset:32
	global_load_dwordx4 v[0:3], v[60:61], off offset:112
	s_nop 0
	global_load_dwordx4 v[4:7], v[60:61], off offset:96
	s_waitcnt vmcnt(0)
	v_pk_mul_f32 v[4:5], v[8:9], v[4:5]
	v_pk_mul_f32 v[8:9], v[18:19], v[40:41] op_sel_hi:[1,0]
	v_cvt_pk_bf16_f32 v4, v4, v5
	v_pk_mul_f32 v[6:7], v[8:9], v[6:7]
	s_nop 0
	v_cvt_pk_bf16_f32 v5, v6, v7
	v_pk_mul_f32 v[6:7], v[12:13], v[40:41] op_sel_hi:[1,0]
	s_nop 0
	v_pk_mul_f32 v[0:1], v[6:7], v[0:1]
	s_nop 0
	v_cvt_pk_bf16_f32 v6, v0, v1
	v_pk_mul_f32 v[0:1], v[14:15], v[40:41] op_sel_hi:[1,0]
	s_nop 0
	v_pk_mul_f32 v[0:1], v[0:1], v[2:3]
	s_nop 0
	v_cvt_pk_bf16_f32 v7, v0, v1
	global_store_dwordx4 v[42:43], v[4:7], off offset:48
	s_barrier
	s_cbranch_scc0 .LBB0_474
	v_readlane_b32 s38, v254, 59
	v_readlane_b32 s39, v254, 60
